# NSA importance pass: the two LDS float atomics per entry replaced by plain stores into two arrays (single writer each) summed at key build; hand-written tile body
# speedup vs baseline: 1.0464x; 1.0152x over previous
; __device__ __forceinline__ v4u pack8(const f32x4& a, const f32x4& b) { return (v4u){cvtpk(a[0], a[1]), cvtpk(a[2], a[3]), cvtpk(b[0], b[1]), cvtpk(b[2], b[3])}; }
; template <int DQK, int MODE> __device__ __forceinline__ void attn_pass(LAS unsigned char* lds, const bf16* K0, int p0, const bf16* K1, int p1, const bf16* V, int pv, int tlo, int thi, ...
;     ...
; #pragma unroll
;     for (int i = 0; i < 2; ++i) {
;         const float lt = rows_sum(l[i]);
;         const float iv = lt > 0.f ? 1.0f / lt : 0.f;
;         mfin[i] = m[i]; linv[i] = iv;
; #pragma unroll
;         for (int dt = 0; dt < 4; ++dt) o[i][dt] = o[i][dt] * iv;
;     }
; __device__ __forceinline__ void nsa_item(LAS unsigned char* lds, const NsaPtrs& P, int b, int g, int qb, int tid) {
;     ...
; #pragma unroll
;     for (int i = 0; i < 2; ++i) { const float gc = P.GATES[((size_t)b * T + tpos[i]) * 24 + g * 12 + hh * 3 + 0];
;         ocl[(i * 2 + 0) * NTHREADS + tid] = pack8(o[i][0] * gc, o[i][1] * gc); ocl[(i * 2 + 1) * NTHREADS + tid] = pack8(o[i][2] * gc, o[i][3] * gc); }
;     ...
;     int tid_i = tid; asm volatile("" : "+v"(tid_i)); const int fr_i = tid_i & 15, fq_i = (tid_i & 63) >> 4; asm volatile("" : "+s"(Kc));
;     v4u kpre = *(const v4u*)(Kc + (size_t)(tid_i >> 3) * 64 + 8 * (tid_i & 7));
.LBB0_1018:
	s_add_u32 s56, s54, 0x3600000
	s_addc_u32 s57, s55, 0
	v_mov_b32_e32 v115, v147
	v_lshl_add_u64 v[120:121], s[46:47], 0, v[114:115]
	s_waitcnt vmcnt(0) lgkmcnt(0)
	v_mov_b64_e32 v[48:49], s[56:57]
	v_mad_u64_u32 v[50:51], s[6:7], v120, s84, v[48:49]
	v_mad_i32_i24 v51, v121, s84, v51
	s_lshl_b32 s18, s71, 2
	v_lshl_add_u64 v[50:51], v[50:51], 0, s[18:19]
	v_mov_b32_e32 v153, v147
	v_lshl_add_u64 v[128:129], v[50:51], 0, v[152:153]
	global_load_dword v50, v[128:129], off
	v_mov_b32_e32 v51, v104
	v_mov_b32_e32 v52, v105
	s_nop 0
	v_permlane16_swap_b32_e32 v104, v51
	v_permlane16_swap_b32_e32 v105, v52
	v_add_f32_e32 v53, v104, v51
	v_add_f32_e32 v52, v105, v52
	v_mov_b32_e32 v55, v53
	v_mov_b32_e32 v54, v52
	s_nop 0
	v_permlane32_swap_b32_e32 v53, v55
	v_permlane32_swap_b32_e32 v52, v54
	v_pk_add_f32 v[52:53], v[52:53], v[54:55]
	v_mov_b32_e32 v117, v147
	v_div_scale_f32 v51, s[6:7], v53, v53, 1.0
	v_lshl_add_u64 v[118:119], s[46:47], 0, v[116:117]
	v_rcp_f32_e32 v54, v51
	v_mad_u64_u32 v[48:49], s[6:7], v118, s84, v[48:49]
	v_mad_i32_i24 v49, v119, s84, v49
	v_lshl_add_u64 v[48:49], v[48:49], 0, s[18:19]
	v_lshl_add_u64 v[126:127], v[48:49], 0, v[152:153]
	v_fma_f32 v48, -v51, v54, 1.0
	v_div_scale_f32 v55, vcc, 1.0, v53, 1.0
	v_fmac_f32_e32 v54, v48, v54
	v_mul_f32_e32 v48, v55, v54
	v_fma_f32 v49, -v51, v48, v55
	v_fmac_f32_e32 v48, v49, v54
	v_fma_f32 v49, -v51, v48, v55
	v_div_fmas_f32 v48, v49, v54, v48
	v_div_fixup_f32 v48, v48, v53, 1.0
	v_cmp_lt_f32_e32 vcc, 0, v53
	v_mad_u64_u32 v[124:125], s[6:7], v120, s84, 0
	s_nop 0
	v_cndmask_b32_e32 v64, 0, v48, vcc
	v_pk_mul_f32 v[44:45], v[44:45], v[64:65] op_sel_hi:[1,0]
	v_pk_mul_f32 v[46:47], v[46:47], v[64:65] op_sel_hi:[1,0]
	v_pk_mul_f32 v[40:41], v[40:41], v[64:65] op_sel_hi:[1,0]
	v_pk_mul_f32 v[42:43], v[42:43], v[64:65] op_sel_hi:[1,0]
	v_pk_mul_f32 v[36:37], v[36:37], v[64:65] op_sel_hi:[1,0]
	v_pk_mul_f32 v[38:39], v[38:39], v[64:65] op_sel_hi:[1,0]
	v_pk_mul_f32 v[32:33], v[32:33], v[64:65] op_sel_hi:[1,0]
	v_pk_mul_f32 v[34:35], v[34:35], v[64:65] op_sel_hi:[1,0]
	v_mad_u64_u32 v[122:123], s[6:7], v118, s84, 0
	v_mad_i32_i24 v125, v121, s84, v125
	v_mad_i32_i24 v123, v119, s84, v123
	s_mov_b32 s10, 0
	s_mov_b32 s11, 0
	s_waitcnt vmcnt(0) lgkmcnt(0)
	v_pk_mul_f32 v[46:47], v[50:51], v[46:47] op_sel_hi:[0,1]
	v_pk_mul_f32 v[44:45], v[50:51], v[44:45] op_sel_hi:[0,1]
	v_pk_mul_f32 v[42:43], v[50:51], v[42:43] op_sel_hi:[0,1]
	v_pk_mul_f32 v[40:41], v[50:51], v[40:41] op_sel_hi:[0,1]
	v_pk_mul_f32 v[38:39], v[50:51], v[38:39] op_sel_hi:[0,1]
	v_pk_mul_f32 v[36:37], v[50:51], v[36:37] op_sel_hi:[0,1]
	v_pk_mul_f32 v[48:49], v[50:51], v[34:35] op_sel_hi:[0,1]
	v_pk_mul_f32 v[50:51], v[50:51], v[32:33] op_sel_hi:[0,1]
	v_cvt_pk_bf16_f32 v32, v44, v45
	v_cvt_pk_bf16_f32 v33, v46, v47
	v_cvt_pk_bf16_f32 v34, v40, v41
	v_cvt_pk_bf16_f32 v35, v42, v43
	v_cvt_pk_bf16_f32 v36, v36, v37
	v_cvt_pk_bf16_f32 v37, v38, v39
	v_cvt_pk_bf16_f32 v38, v50, v51
	v_cvt_pk_bf16_f32 v39, v48, v49
	ds_write_b128 v173, v[32:35]
	ds_write_b128 v174, v[36:39]
	global_load_dword v32, v[126:127], off
	v_div_scale_f32 v33, s[6:7], v52, v52, 1.0
	v_rcp_f32_e32 v34, v33
	v_div_scale_f32 v35, vcc, 1.0, v52, 1.0
	v_mov_b32_e32 v36, v144
	v_fma_f32 v37, -v33, v34, 1.0
	v_fmac_f32_e32 v34, v37, v34
	v_mul_f32_e32 v37, v35, v34
	v_fma_f32 v38, -v33, v37, v35
	v_fmac_f32_e32 v37, v38, v34
	v_fma_f32 v33, -v33, v37, v35
	v_div_fmas_f32 v33, v33, v34, v37
	v_div_fixup_f32 v33, v33, v52, 1.0
	v_cmp_lt_f32_e32 vcc, 0, v52
	s_nop 1
	v_cndmask_b32_e32 v66, 0, v33, vcc
	v_pk_mul_f32 v[28:29], v[28:29], v[66:67] op_sel_hi:[1,0]
	v_pk_mul_f32 v[30:31], v[30:31], v[66:67] op_sel_hi:[1,0]
	v_pk_mul_f32 v[24:25], v[24:25], v[66:67] op_sel_hi:[1,0]
	v_pk_mul_f32 v[26:27], v[26:27], v[66:67] op_sel_hi:[1,0]
	v_pk_mul_f32 v[20:21], v[20:21], v[66:67] op_sel_hi:[1,0]
	v_pk_mul_f32 v[22:23], v[22:23], v[66:67] op_sel_hi:[1,0]
	v_pk_mul_f32 v[16:17], v[16:17], v[66:67] op_sel_hi:[1,0]
	v_pk_mul_f32 v[18:19], v[18:19], v[66:67] op_sel_hi:[1,0]
	s_waitcnt vmcnt(0) lgkmcnt(0)
	v_pk_mul_f32 v[30:31], v[32:33], v[30:31] op_sel_hi:[0,1]
	v_pk_mul_f32 v[28:29], v[32:33], v[28:29] op_sel_hi:[0,1]
	v_pk_mul_f32 v[26:27], v[32:33], v[26:27] op_sel_hi:[0,1]
	v_pk_mul_f32 v[24:25], v[32:33], v[24:25] op_sel_hi:[0,1]
	v_pk_mul_f32 v[20:21], v[32:33], v[20:21] op_sel_hi:[0,1]
	v_pk_mul_f32 v[22:23], v[32:33], v[22:23] op_sel_hi:[0,1]
	v_pk_mul_f32 v[34:35], v[32:33], v[18:19] op_sel_hi:[0,1]
	v_pk_mul_f32 v[32:33], v[32:33], v[16:17] op_sel_hi:[0,1]
	v_cvt_pk_bf16_f32 v16, v28, v29
	v_cvt_pk_bf16_f32 v17, v30, v31
	v_cvt_pk_bf16_f32 v18, v24, v25
	v_cvt_pk_bf16_f32 v19, v26, v27
	v_cvt_pk_bf16_f32 v20, v20, v21
	v_cvt_pk_bf16_f32 v21, v22, v23
	v_cvt_pk_bf16_f32 v22, v32, v33
	v_cvt_pk_bf16_f32 v23, v34, v35
	ds_write_b128 v175, v[16:19]
	ds_write_b128 v176, v[20:23]
	s_nop 0
	v_ashrrev_i32_e32 v20, 3, v36
	v_ashrrev_i32_e32 v21, 31, v20
	v_lshlrev_b32_e32 v18, 4, v36
	v_lshlrev_b64 v[22:23], 7, v[20:21]
	v_lshl_add_u64 v[16:17], s[14:15], 0, v[22:23]
	v_and_b32_e32 v146, 0x70, v18
	v_lshl_add_u64 v[16:17], v[16:17], 0, v[146:147]
	global_load_dwordx4 v[16:19], v[16:17], off
	v_lshlrev_b32_e32 v26, 7, v20
	v_lshrrev_b32_e32 v20, 1, v20
	v_xor_b32_e32 v20, v20, v36
	v_lshlrev_b32_e32 v20, 4, v20
	v_and_b32_e32 v20, 0x70, v20
	v_lshrrev_b32_e32 v24, 4, v36
	v_bfe_u32 v25, v36, 4, 2
	v_add_u32_e32 v27, 0, v20
	v_bfe_u32 v20, v36, 1, 3
	v_bitop3_b32 v24, v24, v20, 3 bitop3:0x6c
	v_bitop3_b32 v20, v25, v20, 4 bitop3:0x36
	v_lshlrev_b32_e32 v29, 4, v20
	v_and_b32_e32 v20, 7, v36
	v_and_b32_e32 v21, 15, v36
	v_lshl_or_b32 v22, v20, 4, v22
	v_lshl_add_u32 v28, v21, 7, 0
	v_lshlrev_b32_e32 v24, 4, v24
	v_cmp_gt_u32_e32 vcc, 4, v21
	v_lshl_add_u64 v[20:21], s[14:15], 0, v[22:23]
	v_lshlrev_b32_e32 v65, 6, v25
	v_lshl_add_u64 v[68:69], v[20:21], 0, s[38:39]
	v_lshl_add_u32 v67, v25, 2, v182
	v_add_u32_e32 v70, v27, v26
	v_add_u32_e32 v71, v28, v24
	v_add_u32_e32 v72, v28, v29
	v_lshlrev_b32_e32 v52, 4, v144
	v_add_u32_e32 v52, 0x2000, v52
	v_mov_b32_e32 v220, 0
	v_mov_b32_e32 v221, 0
	v_mov_b32_e32 v222, 0
	v_mov_b32_e32 v223, 0
	s_waitcnt lgkmcnt(0)
	s_barrier
	ds_write_b128 v52, v[220:223]
	ds_write_b128 v52, v[220:223] offset:8192
	ds_write_b128 v52, v[220:223] offset:16384
	ds_write_b128 v52, v[220:223] offset:24576
	v_cmp_gt_u32_e64 s[12:13], 64, v144
	s_nop 1
	s_and_saveexec_b64 s[14:15], s[12:13]
	ds_write_b128 v52, v[220:223] offset:32768
	s_or_b64 exec, exec, s[14:15]
	s_branch .LBB0_1020

; __device__ __forceinline__ void nsa_item(LAS unsigned char* lds, const NsaPtrs& P, int b, int g, int qb, int tid) {
;     ...
;                 if (fr_i < 4) { const int jp = 16 * t + 4 * ss + fq_i;
;                     __hip_atomic_fetch_add(imp + tok[i] * ISTR + jp, a, __ATOMIC_RELAXED, __HIP_MEMORY_SCOPE_WORKGROUP);
;                     __hip_atomic_fetch_add(imp + tok[i] * ISTR + jp + 1, b3, __ATOMIC_RELAXED, __HIP_MEMORY_SCOPE_WORKGROUP); }
.Limp_store:
	s_and_b64 exec, exec, vcc
	s_cbranch_execz .LBB0_1019
	v_subrev_u32_e32 v56, 0x10400, v67
	ds_write_b32 v67, v220
	ds_write_b32 v56, v223 offset:4
	ds_write_b32 v67, v224 offset:16
	ds_write_b32 v56, v227 offset:20
	ds_write_b32 v67, v228 offset:32
	ds_write_b32 v56, v231 offset:36
	ds_write_b32 v67, v232 offset:48
	ds_write_b32 v56, v235 offset:52
	ds_write_b32 v67, v236 offset:2112
	ds_write_b32 v56, v239 offset:2116
	ds_write_b32 v67, v240 offset:2128
	ds_write_b32 v56, v243 offset:2132
	ds_write_b32 v67, v244 offset:2144
	ds_write_b32 v56, v247 offset:2148
	ds_write_b32 v67, v204 offset:2160
	ds_write_b32 v56, v207 offset:2164
	s_branch .LBB0_1019

; #define LAS __attribute__((address_space(3)))
; __device__ __forceinline__ void nsa_item(LAS unsigned char* lds, const NsaPtrs& P, int b, int g, int qb, int tid) {
;     ...
;         int tid_k = tid; asm volatile("" : "+v"(tid_k)); const int tk = tid_k >> 3, part = tid_k & 7;
;         unsigned v[16]; int cnt[16];
;         LAS unsigned* impu = (LAS unsigned*)imp;
; #pragma unroll
;         for (int jj = 0; jj < 16; ++jj) { const int j = part * 16 + jj; const bool forced = (j == 0) || (j == qb) || (j == qb - 1);
;             const unsigned key = forced ? 0x7fffff80u : (__float_as_uint(fmaxf(imp[tk * ISTR + j], 0.f)) & 0xffffff80u); v[jj] = key | (unsigned)(127 - j); cnt[jj] = 0; }
.LBB0_1039:
	v_mov_b32_e32 v32, v144
	s_waitcnt lgkmcnt(0)
	s_barrier
	s_add_i32 s6, 0, 0x12400
	v_lshrrev_b32_e32 v0, 3, v32
	v_and_b32_e32 v1, 7, v32
	v_lshlrev_b32_e32 v33, 4, v1
	v_mul_lo_u32 v43, v0, s3
	s_add_i32 s87, s72, -1
	v_add_u32_e32 v49, s6, v43
	v_cmp_ne_u32_e32 vcc, 0, v1
	v_cmp_ne_u32_e64 s[6:7], s72, v33
	s_and_b64 s[6:7], vcc, s[6:7]
	v_cmp_ne_u32_e32 vcc, s87, v33
	s_and_b64 s[8:9], s[6:7], vcc
	v_mov_b32_e32 v5, 0x7fffff80
	v_lshl_add_u32 v0, v33, 2, v49
	ds_read_b128 v[56:59], v0
	ds_read_b128 v[60:63], v0 offset:16
	ds_read_b128 v[64:67], v0 offset:32
	ds_read_b128 v[68:71], v0 offset:48
	v_subrev_u32_e32 v72, 0x10400, v0
	ds_read_b128 v[76:79], v72
	ds_read_b128 v[80:83], v72 offset:16
	ds_read_b128 v[84:87], v72 offset:32
	ds_read_b128 v[88:91], v72 offset:48
	s_waitcnt lgkmcnt(0)
	v_add_f32_e32 v56, v56, v76
	v_add_f32_e32 v57, v57, v77
	v_add_f32_e32 v58, v58, v78
	v_add_f32_e32 v59, v59, v79
	v_add_f32_e32 v60, v60, v80
	v_add_f32_e32 v61, v61, v81
	v_add_f32_e32 v62, v62, v82
	v_add_f32_e32 v63, v63, v83
	v_add_f32_e32 v64, v64, v84
	v_add_f32_e32 v65, v65, v85
	v_add_f32_e32 v66, v66, v86
	v_add_f32_e32 v67, v67, v87
	v_add_f32_e32 v68, v68, v88
	v_add_f32_e32 v69, v69, v89
	v_add_f32_e32 v70, v70, v90
	v_add_f32_e32 v71, v71, v91
	v_mov_b32_e32 v3, 0x7fffff80
	s_and_saveexec_b64 s[6:7], s[8:9]
	s_cbranch_execz .LBB0_1041
	v_mov_b32_e32 v2, v56
	v_max_f32_e32 v2, v2, v2
	v_max_f32_e32 v2, 0, v2
	v_and_b32_e32 v3, 0xffffff80, v2
.LBB0_1041:
	s_or_b64 exec, exec, s[6:7]
	v_or_b32_e32 v7, 1, v33
	v_cmp_ne_u32_e32 vcc, s72, v7
	v_cmp_ne_u32_e64 s[6:7], s87, v7
	s_and_b64 s[8:9], vcc, s[6:7]
	s_and_saveexec_b64 s[6:7], s[8:9]
	s_cbranch_execz .LBB0_1043
	v_mov_b32_e32 v2, v57
	v_max_f32_e32 v2, v2, v2
	v_max_f32_e32 v2, 0, v2
	v_and_b32_e32 v5, 0xffffff80, v2
.LBB0_1043:
	s_or_b64 exec, exec, s[6:7]
	v_or_b32_e32 v34, 2, v33
	v_cmp_ne_u32_e32 vcc, s72, v34
	v_cmp_ne_u32_e64 s[6:7], s87, v34
	s_and_b64 s[8:9], vcc, s[6:7]
	v_mov_b32_e32 v11, 0x7fffff80
	v_mov_b32_e32 v9, 0x7fffff80
	s_and_saveexec_b64 s[6:7], s[8:9]
	s_cbranch_execz .LBB0_1045
	v_mov_b32_e32 v2, v58
	v_max_f32_e32 v2, v2, v2
	v_max_f32_e32 v2, 0, v2
	v_and_b32_e32 v9, 0xffffff80, v2
.LBB0_1045:
	s_or_b64 exec, exec, s[6:7]
	v_or_b32_e32 v35, 3, v33
	v_cmp_ne_u32_e32 vcc, s72, v35
	v_cmp_ne_u32_e64 s[6:7], s87, v35
	s_and_b64 s[8:9], vcc, s[6:7]
	s_and_saveexec_b64 s[6:7], s[8:9]
	s_cbranch_execz .LBB0_1047
	v_mov_b32_e32 v2, v59
	v_max_f32_e32 v2, v2, v2
	v_max_f32_e32 v2, 0, v2
	v_and_b32_e32 v11, 0xffffff80, v2
.LBB0_1047:
	s_or_b64 exec, exec, s[6:7]
	v_or_b32_e32 v36, 4, v33
	v_cmp_ne_u32_e32 vcc, s72, v36
	v_cmp_ne_u32_e64 s[6:7], s87, v36
	s_and_b64 s[8:9], vcc, s[6:7]
	v_mov_b32_e32 v12, 0x7fffff80
	v_mov_b32_e32 v8, 0x7fffff80
	s_and_saveexec_b64 s[6:7], s[8:9]
	s_cbranch_execz .LBB0_1049
	v_mov_b32_e32 v2, v60
	v_max_f32_e32 v2, v2, v2
	v_max_f32_e32 v2, 0, v2
	v_and_b32_e32 v8, 0xffffff80, v2
.LBB0_1049:
	s_or_b64 exec, exec, s[6:7]
	v_or_b32_e32 v37, 5, v33
	v_cmp_ne_u32_e32 vcc, s72, v37
	v_cmp_ne_u32_e64 s[6:7], s87, v37
	s_and_b64 s[8:9], vcc, s[6:7]
	s_and_saveexec_b64 s[6:7], s[8:9]
	s_cbranch_execz .LBB0_1051
	v_mov_b32_e32 v2, v61
	v_max_f32_e32 v2, v2, v2
	v_max_f32_e32 v2, 0, v2
	v_and_b32_e32 v12, 0xffffff80, v2
.LBB0_1051:
	s_or_b64 exec, exec, s[6:7]
	v_or_b32_e32 v38, 6, v33
	v_cmp_ne_u32_e32 vcc, s72, v38
	v_cmp_ne_u32_e64 s[6:7], s87, v38
	s_and_b64 s[8:9], vcc, s[6:7]
	v_mov_b32_e32 v13, 0x7fffff80
	v_mov_b32_e32 v10, 0x7fffff80
	s_and_saveexec_b64 s[6:7], s[8:9]
	s_cbranch_execz .LBB0_1053
	v_mov_b32_e32 v2, v62
	v_max_f32_e32 v2, v2, v2
	v_max_f32_e32 v2, 0, v2
	v_and_b32_e32 v10, 0xffffff80, v2
.LBB0_1053:
	s_or_b64 exec, exec, s[6:7]
	v_or_b32_e32 v39, 7, v33
	v_cmp_ne_u32_e32 vcc, s72, v39
	v_cmp_ne_u32_e64 s[6:7], s87, v39
	s_and_b64 s[8:9], vcc, s[6:7]
	s_and_saveexec_b64 s[6:7], s[8:9]
	s_cbranch_execz .LBB0_1055
	v_mov_b32_e32 v2, v63
	v_max_f32_e32 v2, v2, v2
	v_max_f32_e32 v2, 0, v2
	v_and_b32_e32 v13, 0xffffff80, v2
.LBB0_1055:
	s_or_b64 exec, exec, s[6:7]
	v_or_b32_e32 v40, 8, v33
	v_cmp_ne_u32_e32 vcc, s72, v40
	v_cmp_ne_u32_e64 s[6:7], s87, v40
	s_and_b64 s[8:9], vcc, s[6:7]
	v_mov_b32_e32 v14, 0x7fffff80
	v_mov_b32_e32 v4, 0x7fffff80
	s_and_saveexec_b64 s[6:7], s[8:9]
	s_cbranch_execz .LBB0_1057
	v_mov_b32_e32 v2, v64
	v_max_f32_e32 v2, v2, v2
	v_max_f32_e32 v2, 0, v2
	v_and_b32_e32 v4, 0xffffff80, v2
.LBB0_1057:
	s_or_b64 exec, exec, s[6:7]
	v_or_b32_e32 v41, 9, v33
	v_cmp_ne_u32_e32 vcc, s72, v41
	v_cmp_ne_u32_e64 s[6:7], s87, v41
	s_and_b64 s[8:9], vcc, s[6:7]
	s_and_saveexec_b64 s[6:7], s[8:9]
	s_cbranch_execz .LBB0_1059
	v_mov_b32_e32 v2, v65
	v_max_f32_e32 v2, v2, v2
	v_max_f32_e32 v2, 0, v2
	v_and_b32_e32 v14, 0xffffff80, v2
.LBB0_1059:
	s_or_b64 exec, exec, s[6:7]
	v_or_b32_e32 v42, 10, v33
	v_cmp_ne_u32_e32 vcc, s72, v42
	v_cmp_ne_u32_e64 s[6:7], s87, v42
	s_and_b64 s[8:9], vcc, s[6:7]
	v_mov_b32_e32 v15, 0x7fffff80
	v_mov_b32_e32 v6, 0x7fffff80
	s_and_saveexec_b64 s[6:7], s[8:9]
	s_cbranch_execz .LBB0_1061
	v_mov_b32_e32 v2, v66
	v_max_f32_e32 v2, v2, v2
	v_max_f32_e32 v2, 0, v2
	v_and_b32_e32 v6, 0xffffff80, v2
.LBB0_1061:
	s_or_b64 exec, exec, s[6:7]
	v_or_b32_e32 v44, 11, v33
	v_cmp_ne_u32_e32 vcc, s72, v44
	v_cmp_ne_u32_e64 s[6:7], s87, v44
	s_and_b64 s[8:9], vcc, s[6:7]
	s_and_saveexec_b64 s[6:7], s[8:9]
	s_cbranch_execz .LBB0_1063
	v_mov_b32_e32 v2, v67
	v_max_f32_e32 v2, v2, v2
	v_max_f32_e32 v2, 0, v2
	v_and_b32_e32 v15, 0xffffff80, v2
.LBB0_1063:
	s_or_b64 exec, exec, s[6:7]
	v_or_b32_e32 v45, 12, v33
	v_cmp_ne_u32_e32 vcc, s72, v45
	v_cmp_ne_u32_e64 s[6:7], s87, v45
	s_and_b64 s[8:9], vcc, s[6:7]
	s_waitcnt vmcnt(0)
	v_mov_b32_e32 v16, 0x7fffff80
	v_mov_b32_e32 v17, 0x7fffff80
	s_and_saveexec_b64 s[6:7], s[8:9]
	s_cbranch_execz .LBB0_1065
	v_mov_b32_e32 v2, v68
	v_max_f32_e32 v2, v2, v2
	v_max_f32_e32 v2, 0, v2
	v_and_b32_e32 v17, 0xffffff80, v2
.LBB0_1065:
	s_or_b64 exec, exec, s[6:7]
	v_or_b32_e32 v46, 13, v33
	v_cmp_ne_u32_e32 vcc, s72, v46
	v_cmp_ne_u32_e64 s[6:7], s87, v46
	s_and_b64 s[8:9], vcc, s[6:7]
	s_and_saveexec_b64 s[6:7], s[8:9]
	s_cbranch_execz .LBB0_1067
	v_mov_b32_e32 v2, v69
	v_max_f32_e32 v2, v2, v2
	v_max_f32_e32 v2, 0, v2
	v_and_b32_e32 v16, 0xffffff80, v2
.LBB0_1067:
	s_or_b64 exec, exec, s[6:7]
	v_or_b32_e32 v47, 14, v33
	v_cmp_ne_u32_e32 vcc, s72, v47
	v_cmp_ne_u32_e64 s[6:7], s87, v47
	s_and_b64 s[8:9], vcc, s[6:7]
	v_mov_b32_e32 v19, 0x7fffff80
	v_mov_b32_e32 v2, 0x7fffff80
	s_and_saveexec_b64 s[6:7], s[8:9]
	s_cbranch_execz .LBB0_1069
	v_mov_b32_e32 v2, v70
	v_max_f32_e32 v2, v2, v2
	v_max_f32_e32 v2, 0, v2
	v_and_b32_e32 v2, 0xffffff80, v2
.LBB0_1069:
	s_or_b64 exec, exec, s[6:7]
	v_or_b32_e32 v48, 15, v33
	v_cmp_ne_u32_e32 vcc, s72, v48
	v_cmp_ne_u32_e64 s[6:7], s87, v48
	s_and_b64 s[8:9], vcc, s[6:7]
	s_and_saveexec_b64 s[6:7], s[8:9]
	s_cbranch_execz .LBB0_1071
	v_mov_b32_e32 v0, v71
	v_max_f32_e32 v0, v0, v0
	v_max_f32_e32 v0, 0, v0
	v_and_b32_e32 v19, 0xffffff80, v0
